# v081: v080 + nt (streaming) hint on the bf16 cache stores of the pre2 gather blocks, so they do not evict the k_inv operands from L2
# speedup vs baseline: 1.0088x; 1.0084x over previous
.LBB0_422:
	s_waitcnt lgkmcnt(0)
	v_add_co_u32_e32 v38, vcc, 0xffffc000, v86
	v_lshl_add_u64 v[92:93], s[26:27], 0, v[88:89]
	s_nop 0
	v_addc_co_u32_e32 v39, vcc, -1, v87, vcc
	global_load_dwordx4 v[70:73], v[38:39], off offset:-1024 nt
	global_load_dwordx4 v[66:69], v[38:39], off nt
	v_add_co_u32_e32 v38, vcc, 0xffffd000, v86
	s_waitcnt vmcnt(10)
	v_cvt_pk_bf16_f32 v94, v2, v3
	v_addc_co_u32_e32 v39, vcc, -1, v87, vcc
	global_load_dwordx4 v[62:65], v[38:39], off offset:-3072 nt
	global_load_dwordx4 v[58:61], v[38:39], off offset:-2048 nt
	global_load_dwordx4 v[54:57], v[38:39], off offset:-1024 nt
	global_load_dwordx4 v[50:53], v[38:39], off nt
	v_add_co_u32_e32 v38, vcc, 0xffffe000, v86
	v_cvt_pk_bf16_f32 v95, v4, v5
	s_nop 0
	v_addc_co_u32_e32 v39, vcc, -1, v87, vcc
	global_load_dwordx4 v[46:49], v[38:39], off offset:-3072 nt
	global_load_dwordx4 v[42:45], v[38:39], off offset:-2048 nt
	s_nop 0
	global_load_dwordx4 v[38:41], v[38:39], off offset:-1024 nt
	v_add_co_u32_e32 v96, vcc, 0x1d123000, v92
	s_waitcnt vmcnt(14)
	v_cvt_pk_bf16_f32 v98, v14, v15
	v_addc_co_u32_e32 v97, vcc, 0, v93, vcc
	global_store_dwordx2 v[96:97], v[94:95], off offset:3072 nt
	v_cvt_pk_bf16_f32 v94, v6, v7
	v_cvt_pk_bf16_f32 v95, v8, v9
	v_and_b32_e32 v75, 0xffff0000, v94
	global_store_dwordx2 v[96:97], v[94:95], off offset:3584 nt
	v_lshlrev_b32_e32 v1, 16, v94
	v_mul_f32_e32 v75, v75, v75
	v_and_b32_e32 v94, 0xffff0000, v95
	v_fmac_f32_e32 v75, v1, v1
	v_lshlrev_b32_e32 v1, 16, v95
	v_mul_f32_e32 v94, v94, v94
	v_fmac_f32_e32 v94, v1, v1
	v_add_f32_e32 v1, v75, v94
	v_cvt_pk_bf16_f32 v94, v10, v11
	v_cvt_pk_bf16_f32 v95, v12, v13
	v_and_b32_e32 v96, 0xffff0000, v94
	v_lshlrev_b32_e32 v75, 16, v94
	v_mul_f32_e32 v96, v96, v96
	v_and_b32_e32 v97, 0xffff0000, v95
	v_fmac_f32_e32 v96, v75, v75
	v_lshlrev_b32_e32 v75, 16, v95
	v_mul_f32_e32 v97, v97, v97
	v_fmac_f32_e32 v97, v75, v75
	v_cndmask_b32_e64 v1, 0, v1, s[8:9]
	v_add_f32_e32 v75, v96, v97
	v_cvt_pk_bf16_f32 v99, v16, v17
	v_and_b32_e32 v96, 0xffff0000, v98
	v_cndmask_b32_e64 v1, v1, v75, s[10:11]
	v_lshlrev_b32_e32 v75, 16, v98
	v_mul_f32_e32 v96, v96, v96
	v_and_b32_e32 v97, 0xffff0000, v99
	v_fmac_f32_e32 v96, v75, v75
	v_lshlrev_b32_e32 v75, 16, v99
	v_mul_f32_e32 v97, v97, v97
	v_fmac_f32_e32 v97, v75, v75
	s_waitcnt vmcnt(15)
	v_cvt_pk_bf16_f32 v100, v18, v19
	v_add_f32_e32 v75, v96, v97
	v_cvt_pk_bf16_f32 v101, v20, v21
	v_and_b32_e32 v96, 0xffff0000, v100
	v_cndmask_b32_e64 v1, v1, v75, s[12:13]
	v_lshlrev_b32_e32 v75, 16, v100
	v_mul_f32_e32 v96, v96, v96
	v_and_b32_e32 v97, 0xffff0000, v101
	v_fmac_f32_e32 v96, v75, v75
	v_lshlrev_b32_e32 v75, 16, v101
	v_mul_f32_e32 v97, v97, v97
	v_fmac_f32_e32 v97, v75, v75
	s_waitcnt vmcnt(14)
	v_cvt_pk_bf16_f32 v102, v22, v23
	v_add_f32_e32 v75, v96, v97
	v_cvt_pk_bf16_f32 v103, v24, v25
	v_and_b32_e32 v96, 0xffff0000, v102
	v_cndmask_b32_e64 v1, v1, v75, s[14:15]
	v_lshlrev_b32_e32 v75, 16, v102
	v_mul_f32_e32 v96, v96, v96
	v_and_b32_e32 v97, 0xffff0000, v103
	v_fmac_f32_e32 v96, v75, v75
	v_lshlrev_b32_e32 v75, 16, v103
	v_mul_f32_e32 v97, v97, v97
	v_fmac_f32_e32 v97, v75, v75
	s_waitcnt vmcnt(13)
	v_cvt_pk_bf16_f32 v104, v26, v27
	v_add_f32_e32 v75, v96, v97
	v_cvt_pk_bf16_f32 v105, v28, v29
	v_and_b32_e32 v96, 0xffff0000, v104
	v_cndmask_b32_e64 v1, v1, v75, s[16:17]
	v_lshlrev_b32_e32 v75, 16, v104
	v_mul_f32_e32 v96, v96, v96
	v_and_b32_e32 v97, 0xffff0000, v105
	v_fmac_f32_e32 v96, v75, v75
	v_lshlrev_b32_e32 v75, 16, v105
	v_mul_f32_e32 v97, v97, v97
	v_fmac_f32_e32 v97, v75, v75
	s_waitcnt vmcnt(12)
	v_cvt_pk_bf16_f32 v106, v30, v31
	v_add_f32_e32 v75, v96, v97
	v_cvt_pk_bf16_f32 v107, v32, v33
	v_and_b32_e32 v96, 0xffff0000, v106
	v_cndmask_b32_e64 v1, v1, v75, s[18:19]
	v_lshlrev_b32_e32 v75, 16, v106
	v_mul_f32_e32 v96, v96, v96
	v_and_b32_e32 v97, 0xffff0000, v107
	v_fmac_f32_e32 v96, v75, v75
	v_lshlrev_b32_e32 v75, 16, v107
	v_mul_f32_e32 v97, v97, v97
	v_fmac_f32_e32 v97, v75, v75
	s_waitcnt vmcnt(11)
	v_cvt_pk_bf16_f32 v108, v34, v35
	v_add_f32_e32 v75, v96, v97
	v_cvt_pk_bf16_f32 v109, v36, v37
	v_and_b32_e32 v96, 0xffff0000, v108
	v_cndmask_b32_e64 v1, v1, v75, s[20:21]
	v_lshlrev_b32_e32 v75, 16, v108
	v_mul_f32_e32 v96, v96, v96
	v_and_b32_e32 v97, 0xffff0000, v109
	v_fmac_f32_e32 v96, v75, v75
	v_lshlrev_b32_e32 v75, 16, v109
	v_mul_f32_e32 v97, v97, v97
	v_fmac_f32_e32 v97, v75, v75
	v_add_f32_e32 v75, v96, v97
	v_cndmask_b32_e64 v1, v1, v75, s[22:23]
	ds_swizzle_b32 v75, v1 offset:swizzle(SWAP,1)
	v_add_co_u32_e32 v96, vcc, s33, v92
	s_waitcnt lgkmcnt(0)
	v_add_f32_e32 v1, v1, v75
	ds_swizzle_b32 v75, v1 offset:swizzle(SWAP,2)
	v_addc_co_u32_e32 v97, vcc, 0, v93, vcc
	global_store_dwordx2 v[96:97], v[94:95], off nt
	global_store_dwordx2 v[96:97], v[98:99], off offset:512 nt
	global_store_dwordx2 v[96:97], v[100:101], off offset:1024 nt
	global_store_dwordx2 v[96:97], v[102:103], off offset:1536 nt
	v_lshl_add_u64 v[94:95], s[26:27], 0, v[90:91]
	s_waitcnt lgkmcnt(0)
	v_add_f32_e32 v1, v1, v75
	ds_swizzle_b32 v75, v1 offset:swizzle(SWAP,4)
	global_store_dwordx2 v[96:97], v[104:105], off offset:2048 nt
	global_store_dwordx2 v[96:97], v[106:107], off offset:2560 nt
	global_store_dwordx2 v[96:97], v[108:109], off offset:3072 nt
	s_and_saveexec_b64 s[42:43], s[6:7]
	s_cbranch_execz .LBB0_424
	v_add_co_u32_e32 v98, vcc, 0x34d30000, v94
	s_waitcnt lgkmcnt(0)
	v_add_f32_e32 v1, v1, v75
	v_addc_co_u32_e32 v99, vcc, 0, v95, vcc
	global_store_dword v[98:99], v1, off

.LBB0_426:
	s_waitcnt vmcnt(16)
	v_cvt_pk_bf16_f32 v66, v66, v67
	v_cvt_pk_bf16_f32 v67, v68, v69
	v_and_b32_e32 v68, 0xffff0000, v66
	v_lshlrev_b32_e32 v1, 16, v66
	v_mul_f32_e32 v68, v68, v68
	v_and_b32_e32 v69, 0xffff0000, v67
	v_fmac_f32_e32 v68, v1, v1
	v_lshlrev_b32_e32 v1, 16, v67
	v_mul_f32_e32 v69, v69, v69
	s_waitcnt vmcnt(15)
	v_cvt_pk_bf16_f32 v62, v62, v63
	v_fmac_f32_e32 v69, v1, v1
	v_cvt_pk_bf16_f32 v63, v64, v65
	v_and_b32_e32 v65, 0xffff0000, v62
	v_add_f32_e32 v1, v68, v69
	v_lshlrev_b32_e32 v64, 16, v62
	v_mul_f32_e32 v65, v65, v65
	v_and_b32_e32 v68, 0xffff0000, v63
	v_fmac_f32_e32 v65, v64, v64
	v_lshlrev_b32_e32 v64, 16, v63
	v_mul_f32_e32 v68, v68, v68
	v_fmac_f32_e32 v68, v64, v64
	s_waitcnt vmcnt(14)
	v_cvt_pk_bf16_f32 v58, v58, v59
	v_cndmask_b32_e64 v1, 0, v1, s[8:9]
	v_add_f32_e32 v64, v65, v68
	v_cvt_pk_bf16_f32 v59, v60, v61
	v_and_b32_e32 v61, 0xffff0000, v58
	v_cndmask_b32_e64 v1, v1, v64, s[10:11]
	v_lshlrev_b32_e32 v60, 16, v58
	v_mul_f32_e32 v61, v61, v61
	v_and_b32_e32 v64, 0xffff0000, v59
	v_fmac_f32_e32 v61, v60, v60
	v_lshlrev_b32_e32 v60, 16, v59
	v_mul_f32_e32 v64, v64, v64
	v_fmac_f32_e32 v64, v60, v60
	s_waitcnt vmcnt(13)
	v_cvt_pk_bf16_f32 v54, v54, v55
	v_add_f32_e32 v60, v61, v64
	v_cvt_pk_bf16_f32 v55, v56, v57
	v_and_b32_e32 v57, 0xffff0000, v54
	v_cndmask_b32_e64 v1, v1, v60, s[12:13]
	v_lshlrev_b32_e32 v56, 16, v54
	v_mul_f32_e32 v57, v57, v57
	v_and_b32_e32 v60, 0xffff0000, v55
	v_fmac_f32_e32 v57, v56, v56
	v_lshlrev_b32_e32 v56, 16, v55
	v_mul_f32_e32 v60, v60, v60
	v_fmac_f32_e32 v60, v56, v56
	s_waitcnt vmcnt(12)
	v_cvt_pk_bf16_f32 v50, v50, v51
	v_add_f32_e32 v56, v57, v60
	v_cvt_pk_bf16_f32 v51, v52, v53
	v_and_b32_e32 v53, 0xffff0000, v50
	v_cndmask_b32_e64 v1, v1, v56, s[14:15]
	v_lshlrev_b32_e32 v52, 16, v50
	v_mul_f32_e32 v53, v53, v53
	v_and_b32_e32 v56, 0xffff0000, v51
	v_fmac_f32_e32 v53, v52, v52
	v_lshlrev_b32_e32 v52, 16, v51
	v_mul_f32_e32 v56, v56, v56
	v_fmac_f32_e32 v56, v52, v52
	s_waitcnt vmcnt(11)
	v_cvt_pk_bf16_f32 v46, v46, v47
	v_add_f32_e32 v52, v53, v56
	v_cvt_pk_bf16_f32 v47, v48, v49
	v_and_b32_e32 v49, 0xffff0000, v46
	v_cndmask_b32_e64 v1, v1, v52, s[16:17]
	v_lshlrev_b32_e32 v48, 16, v46
	v_mul_f32_e32 v49, v49, v49
	v_and_b32_e32 v52, 0xffff0000, v47
	v_fmac_f32_e32 v49, v48, v48
	v_lshlrev_b32_e32 v48, 16, v47
	v_mul_f32_e32 v52, v52, v52
	v_fmac_f32_e32 v52, v48, v48
	s_waitcnt vmcnt(10)
	v_cvt_pk_bf16_f32 v42, v42, v43
	v_add_f32_e32 v48, v49, v52
	v_cvt_pk_bf16_f32 v43, v44, v45
	v_and_b32_e32 v45, 0xffff0000, v42
	v_cndmask_b32_e64 v1, v1, v48, s[18:19]
	v_lshlrev_b32_e32 v44, 16, v42
	v_mul_f32_e32 v45, v45, v45
	v_and_b32_e32 v48, 0xffff0000, v43
	v_fmac_f32_e32 v45, v44, v44
	v_lshlrev_b32_e32 v44, 16, v43
	v_mul_f32_e32 v48, v48, v48
	v_fmac_f32_e32 v48, v44, v44
	v_add_f32_e32 v44, v45, v48
	v_cndmask_b32_e64 v1, v1, v44, s[20:21]
	s_waitcnt vmcnt(9)
	v_cvt_pk_bf16_f32 v44, v38, v39
	v_cvt_pk_bf16_f32 v45, v40, v41
	v_and_b32_e32 v39, 0xffff0000, v44
	v_lshlrev_b32_e32 v38, 16, v44
	v_mul_f32_e32 v39, v39, v39
	v_and_b32_e32 v40, 0xffff0000, v45
	v_fmac_f32_e32 v39, v38, v38
	v_lshlrev_b32_e32 v38, 16, v45
	v_mul_f32_e32 v40, v40, v40
	v_fmac_f32_e32 v40, v38, v38
	v_add_f32_e32 v38, v39, v40
	v_cndmask_b32_e64 v1, v1, v38, s[22:23]
	ds_swizzle_b32 v38, v1 offset:swizzle(SWAP,1)
	v_add_co_u32_e32 v40, vcc, s46, v92
	v_cvt_pk_bf16_f32 v70, v70, v71
	v_cvt_pk_bf16_f32 v71, v72, v73
	s_waitcnt lgkmcnt(0)
	v_add_f32_e32 v1, v1, v38
	ds_swizzle_b32 v38, v1 offset:swizzle(SWAP,2)
	v_addc_co_u32_e32 v41, vcc, 0, v93, vcc
	global_store_dwordx2 v[96:97], v[70:71], off offset:3584 nt
	global_store_dwordx2 v[40:41], v[66:67], off nt
	global_store_dwordx2 v[40:41], v[62:63], off offset:512 nt
	global_store_dwordx2 v[40:41], v[58:59], off offset:1024 nt
	global_store_dwordx2 v[40:41], v[54:55], off offset:1536 nt
	s_waitcnt lgkmcnt(0)
	v_add_f32_e32 v1, v1, v38
	ds_swizzle_b32 v38, v1 offset:swizzle(SWAP,4)
	global_store_dwordx2 v[40:41], v[50:51], off offset:2048 nt
	global_store_dwordx2 v[40:41], v[46:47], off offset:2560 nt
	global_store_dwordx2 v[40:41], v[42:43], off offset:3072 nt
	global_store_dwordx2 v[40:41], v[44:45], off offset:3584 nt
	s_and_saveexec_b64 s[44:45], s[6:7]
	s_cbranch_execz .LBB0_421
	s_waitcnt lgkmcnt(0)
	v_add_f32_e32 v1, v1, v38
	v_add_co_u32_e32 v38, vcc, 0x34d30000, v94
	s_nop 1
	v_addc_co_u32_e32 v39, vcc, 0, v95, vcc
	global_store_dword v[38:39], v1, off offset:32
	s_branch .LBB0_421
